# hgrn_sample_unit: all 16 f/q and 8 v bf16 raw loads of a unit issued together (one wait) instead of one round trip each; plus norm-loop waits at loop bottom
# speedup vs baseline: 1.0168x; 1.0168x over previous
; #define LAS __attribute__((address_space(3)))
; __device__ __forceinline__ float bf2f(unsigned short b) { return __uint_as_float(((unsigned)b) << 16); }
; __device__ __forceinline__ float sigmoidf_(float x) { return __builtin_amdgcn_rcpf(1.0f + __expf(-x)); }
; __device__ __forceinline__ float siluf_(float x) { return x * sigmoidf_(x); }
; __device__ __forceinline__ void hgrn_sample_unit(int unit, const bf16* Z, const float* lbl, const float* S0, float* S1, bf16* HB, LAS unsigned char* lds, int tid) {
;     LAS float* Fl = (LAS float*)lds; LAS float* Kk = Fl + 1024; LAS float* Qq = Fl + 2048; LAS float* Vv = Fl + 3072; LAS float* red = Fl + 4096;
;     const int h = unit & 7, b = unit >> 3; const size_t r0 = (size_t)MP + b * 8;
;     const int dv4 = tid & 31, dkg = tid >> 5; const size_t sb = (size_t)unit * 16384;
;     f32x4 S[8], op[8];
; #pragma unroll
;     for (int i = 0; i < 8; ++i) S[i] = *(const f32x4*)(S0 + sb + (dkg * 8 + i) * 128 + dv4 * 4);
;     if (tid < 128) { const int ch = tid; const float l0 = lbl[h * 128 + ch], l1 = lbl[1024 + h * 128 + ch]; const float lb = 1.0f / (1.0f + __expf(l1 - l0)), omlb = 1.0f - lb;
; #pragma unroll
;         for (int t = 0; t < 8; ++t) { const bf16* zr = Z + (r0 + t) * NIN + h * 128 + ch; const float fraw = bf2f(zr[ZHF]), qraw = bf2f(zr[ZHQ]); const float sg = sigmoidf_(fraw);
;             Fl[t * 128 + ch] = lb + omlb * sg; Kk[t * 128 + ch] = omlb * (1.0f - sg); Qq[t * 128 + ch] = siluf_(qraw); } }
;     else if (tid < 256) { const int ch = tid - 128;
; #pragma unroll
;         for (int t = 0; t < 8; ++t) Vv[t * 128 + ch] = bf2f(Z[(r0 + t) * NIN + ZHI + h * 128 + ch]); }
.LBB0_619:
	s_ashr_i32 s13, s12, 31
	s_lshl_b64 s[4:5], s[12:13], 16
	v_lshl_add_u64 v[2:3], v[42:43], 0, s[4:5]
	global_load_dwordx4 v[30:33], v[2:3], off
	global_load_dwordx4 v[26:29], v[2:3], off offset:512
	global_load_dwordx4 v[22:25], v[2:3], off offset:1024
	global_load_dwordx4 v[18:21], v[2:3], off offset:1536
	global_load_dwordx4 v[14:17], v[2:3], off offset:2048
	global_load_dwordx4 v[10:13], v[2:3], off offset:2560
	global_load_dwordx4 v[6:9], v[2:3], off offset:3072
	s_nop 0
	global_load_dwordx4 v[2:5], v[2:3], off offset:3584
	s_and_b32 s2, s12, -8
	s_ashr_i32 s19, s2, 31
	s_add_u32 s20, s2, 0x4000
	s_addc_u32 s21, s19, 0
	s_lshl_b32 s4, s12, 7
	s_and_b32 s8, s4, 0x380
	v_mov_b64_e32 v[50:51], s[8:9]
	s_and_saveexec_b64 s[4:5], s[0:1]
	s_xor_b64 s[4:5], exec, s[4:5]
	s_cbranch_execz .LBB0_623
	s_and_saveexec_b64 s[14:15], s[6:7]
	s_cbranch_execz .LBB0_622
	s_mul_i32 s22, s21, 0x2c00
	s_mul_hi_u32 s23, s20, 0x2c00
	s_add_i32 s23, s23, s22
	s_mul_i32 s22, s20, 0x2c00
	v_readlane_b32 s26, v255, 0
	v_readlane_b32 s27, v255, 1
	s_add_u32 s22, s26, s22
	s_addc_u32 s23, s27, s23
	s_lshl_b32 s24, s8, 1
	s_add_u32 s22, s22, s24
	s_addc_u32 s23, s23, 0
	s_add_u32 s22, s22, 0x1c00
	s_addc_u32 s23, s23, 0
	global_load_ushort v60, v48, s[22:23]
	s_add_u32 s22, s22, 0x2c00
	s_addc_u32 s23, s23, 0
	global_load_ushort v61, v48, s[22:23]
	s_add_u32 s22, s22, 0x2c00
	s_addc_u32 s23, s23, 0
	global_load_ushort v62, v48, s[22:23]
	s_add_u32 s22, s22, 0x2c00
	s_addc_u32 s23, s23, 0
	global_load_ushort v63, v48, s[22:23]
	s_add_u32 s22, s22, 0x2c00
	s_addc_u32 s23, s23, 0
	global_load_ushort v64, v48, s[22:23]
	s_add_u32 s22, s22, 0x2c00
	s_addc_u32 s23, s23, 0
	global_load_ushort v65, v48, s[22:23]
	s_add_u32 s22, s22, 0x2c00
	s_addc_u32 s23, s23, 0
	global_load_ushort v66, v48, s[22:23]
	s_add_u32 s22, s22, 0x2c00
	s_addc_u32 s23, s23, 0
	global_load_ushort v67, v48, s[22:23]
	s_waitcnt vmcnt(0)
	v_lshlrev_b32_e32 v60, 16, v60
	v_lshlrev_b32_e32 v61, 16, v61
	v_lshlrev_b32_e32 v62, 16, v62
	v_lshlrev_b32_e32 v63, 16, v63
	v_lshlrev_b32_e32 v64, 16, v64
	v_lshlrev_b32_e32 v65, 16, v65
	v_lshlrev_b32_e32 v66, 16, v66
	v_lshlrev_b32_e32 v67, 16, v67
	ds_write2st64_b32 v41, v60, v61 offset0:46 offset1:48
	ds_write2st64_b32 v41, v62, v63 offset0:50 offset1:52
	ds_write2st64_b32 v41, v64, v65 offset0:54 offset1:56
	ds_write2st64_b32 v41, v66, v67 offset0:58 offset1:60

; __device__ __forceinline__ float bf2f(unsigned short b) { return __uint_as_float(((unsigned)b) << 16); }
; __device__ __forceinline__ float sigmoidf_(float x) { return __builtin_amdgcn_rcpf(1.0f + __expf(-x)); }
; __device__ __forceinline__ float siluf_(float x) { return x * sigmoidf_(x); }
; __device__ __forceinline__ void hgrn_sample_unit(int unit, const bf16* Z, const float* lbl, const float* S0, float* S1, bf16* HB, LAS unsigned char* lds, int tid) {
;     ...
;     if (tid < 128) { const int ch = tid; const float l0 = lbl[h * 128 + ch], l1 = lbl[1024 + h * 128 + ch]; const float lb = 1.0f / (1.0f + __expf(l1 - l0)), omlb = 1.0f - lb;
; #pragma unroll
;         for (int t = 0; t < 8; ++t) { const bf16* zr = Z + (r0 + t) * NIN + h * 128 + ch; const float fraw = bf2f(zr[ZHF]), qraw = bf2f(zr[ZHQ]); const float sg = sigmoidf_(fraw);
;             Fl[t * 128 + ch] = lb + omlb * sg; Kk[t * 128 + ch] = omlb * (1.0f - sg); Qq[t * 128 + ch] = siluf_(qraw); } }
.LBB0_623:
	s_or_saveexec_b64 s[4:5], s[4:5]
	s_lshl_b64 s[14:15], s[12:13], 14
	s_xor_b64 exec, exec, s[4:5]
	s_cbranch_execz .LBB0_625
	v_or_b32_e32 v36, s8, v1
	v_readlane_b32 s36, v254, 29
	v_lshlrev_b32_e32 v36, 2, v36
	v_readlane_b32 s38, v254, 31
	v_readlane_b32 s39, v254, 32
	s_lshl_b32 s8, s8, 1
	v_readlane_b32 s37, v254, 30
	v_lshl_add_u64 v[52:53], s[38:39], 0, v[36:37]
	v_add_co_u32_e32 v52, vcc, 0x1000, v52
	s_nop 0
	global_load_dword v36, v36, s[38:39]
	v_addc_co_u32_e32 v53, vcc, 0, v53, vcc
	global_load_dword v51, v[52:53], off
	v_readlane_b32 s40, v254, 33
	v_readlane_b32 s41, v254, 34
	v_readlane_b32 s42, v254, 35
	v_readlane_b32 s43, v254, 36
	v_readlane_b32 s44, v254, 37
	v_readlane_b32 s45, v254, 38
	v_readlane_b32 s46, v254, 39
	v_readlane_b32 s47, v254, 40
	v_readlane_b32 s48, v254, 41
	v_readlane_b32 s49, v254, 42
	v_readlane_b32 s50, v254, 43
	v_readlane_b32 s51, v254, 44
	s_mul_i32 s22, s21, 0x2c00
	s_mul_hi_u32 s23, s20, 0x2c00
	s_add_i32 s23, s23, s22
	s_mul_i32 s22, s20, 0x2c00
	v_readlane_b32 s26, v255, 0
	v_readlane_b32 s27, v255, 1
	v_lshlrev_b32_e32 v78, 1, v1
	s_add_u32 s22, s26, s22
	s_addc_u32 s23, s27, s23
	s_add_u32 s22, s22, s8
	s_addc_u32 s23, s23, 0
	s_add_u32 s22, s22, 0xc00
	s_addc_u32 s23, s23, 0
	global_load_ushort v60, v78, s[22:23]
	global_load_ushort v70, v78, s[22:23] offset:2048
	s_add_u32 s22, s22, 0x2c00
	s_addc_u32 s23, s23, 0
	global_load_ushort v61, v78, s[22:23]
	global_load_ushort v71, v78, s[22:23] offset:2048
	s_add_u32 s22, s22, 0x2c00
	s_addc_u32 s23, s23, 0
	global_load_ushort v62, v78, s[22:23]
	global_load_ushort v72, v78, s[22:23] offset:2048
	s_add_u32 s22, s22, 0x2c00
	s_addc_u32 s23, s23, 0
	global_load_ushort v63, v78, s[22:23]
	global_load_ushort v73, v78, s[22:23] offset:2048
	s_add_u32 s22, s22, 0x2c00
	s_addc_u32 s23, s23, 0
	global_load_ushort v64, v78, s[22:23]
	global_load_ushort v74, v78, s[22:23] offset:2048
	s_add_u32 s22, s22, 0x2c00
	s_addc_u32 s23, s23, 0
	global_load_ushort v65, v78, s[22:23]
	global_load_ushort v75, v78, s[22:23] offset:2048
	s_add_u32 s22, s22, 0x2c00
	s_addc_u32 s23, s23, 0
	global_load_ushort v66, v78, s[22:23]
	global_load_ushort v76, v78, s[22:23] offset:2048
	s_add_u32 s22, s22, 0x2c00
	s_addc_u32 s23, s23, 0
	global_load_ushort v67, v78, s[22:23]
	global_load_ushort v77, v78, s[22:23] offset:2048
	s_waitcnt vmcnt(16)
	v_sub_f32_e32 v36, v51, v36
	v_mul_f32_e32 v36, 0x3fb8aa3b, v36
	v_exp_f32_e32 v36, v36
	s_nop 0
	v_add_f32_e32 v36, 1.0, v36
	v_div_scale_f32 v51, s[22:23], v36, v36, 1.0
	v_rcp_f32_e32 v52, v51
	s_nop 0
	v_fma_f32 v53, -v51, v52, 1.0
	v_fmac_f32_e32 v52, v53, v52
	v_div_scale_f32 v53, vcc, 1.0, v36, 1.0
	v_mul_f32_e32 v54, v53, v52
	v_fma_f32 v55, -v51, v54, v53
	v_fmac_f32_e32 v54, v55, v52
	v_fma_f32 v51, -v51, v54, v53
	v_div_fmas_f32 v51, v51, v52, v54
	v_div_fixup_f32 v51, v51, v36, 1.0
	v_sub_f32_e32 v36, 1.0, v51
	s_waitcnt vmcnt(0)
	v_lshlrev_b32_e32 v70, 16, v70
	v_lshlrev_b32_e32 v60, 16, v60
	v_mul_f32_e32 v52, 0xbfb8aa3b, v70
	v_mul_f32_e32 v53, 0xbfb8aa3b, v60
	v_exp_f32_e32 v52, v52
	v_exp_f32_e32 v53, v53
	s_nop 0
	v_add_f32_e32 v52, 1.0, v52
	v_add_f32_e32 v53, 1.0, v53
	v_rcp_f32_e32 v52, v52
	v_rcp_f32_e32 v53, v53
	s_nop 0
	v_fma_f32 v54, v36, v52, v51
	v_sub_f32_e32 v52, 1.0, v52
	v_mul_f32_e32 v55, v36, v52
	v_mul_f32_e32 v56, v53, v60
	v_lshlrev_b32_e32 v71, 16, v71
	v_lshlrev_b32_e32 v61, 16, v61
	v_mul_f32_e32 v52, 0xbfb8aa3b, v71
	v_mul_f32_e32 v53, 0xbfb8aa3b, v61
	v_exp_f32_e32 v52, v52
	v_exp_f32_e32 v53, v53
	s_nop 0
	v_add_f32_e32 v52, 1.0, v52
	v_add_f32_e32 v53, 1.0, v53
	v_rcp_f32_e32 v52, v52
	v_rcp_f32_e32 v53, v53
	s_nop 0
	v_fma_f32 v57, v36, v52, v51
	v_sub_f32_e32 v52, 1.0, v52
	v_mul_f32_e32 v58, v36, v52
	v_mul_f32_e32 v59, v53, v61
	ds_write2st64_b32 v41, v54, v57 offset0:0 offset1:2
	ds_write2st64_b32 v41, v55, v58 offset0:16 offset1:18
	ds_write2st64_b32 v41, v56, v59 offset0:32 offset1:34
	v_lshlrev_b32_e32 v72, 16, v72
	v_lshlrev_b32_e32 v62, 16, v62
	v_mul_f32_e32 v52, 0xbfb8aa3b, v72
	v_mul_f32_e32 v53, 0xbfb8aa3b, v62
	v_exp_f32_e32 v52, v52
	v_exp_f32_e32 v53, v53
	s_nop 0
	v_add_f32_e32 v52, 1.0, v52
	v_add_f32_e32 v53, 1.0, v53
	v_rcp_f32_e32 v52, v52
	v_rcp_f32_e32 v53, v53
	s_nop 0
	v_fma_f32 v54, v36, v52, v51
	v_sub_f32_e32 v52, 1.0, v52
	v_mul_f32_e32 v55, v36, v52
	v_mul_f32_e32 v56, v53, v62
	v_lshlrev_b32_e32 v73, 16, v73
	v_lshlrev_b32_e32 v63, 16, v63
	v_mul_f32_e32 v52, 0xbfb8aa3b, v73
	v_mul_f32_e32 v53, 0xbfb8aa3b, v63
	v_exp_f32_e32 v52, v52
	v_exp_f32_e32 v53, v53
	s_nop 0
	v_add_f32_e32 v52, 1.0, v52
	v_add_f32_e32 v53, 1.0, v53
	v_rcp_f32_e32 v52, v52
	v_rcp_f32_e32 v53, v53
	s_nop 0
	v_fma_f32 v57, v36, v52, v51
	v_sub_f32_e32 v52, 1.0, v52
	v_mul_f32_e32 v58, v36, v52
	v_mul_f32_e32 v59, v53, v63
	ds_write2st64_b32 v41, v54, v57 offset0:4 offset1:6
	ds_write2st64_b32 v41, v55, v58 offset0:20 offset1:22
	ds_write2st64_b32 v41, v56, v59 offset0:36 offset1:38
	v_lshlrev_b32_e32 v74, 16, v74
	v_lshlrev_b32_e32 v64, 16, v64
	v_mul_f32_e32 v52, 0xbfb8aa3b, v74
	v_mul_f32_e32 v53, 0xbfb8aa3b, v64
	v_exp_f32_e32 v52, v52
	v_exp_f32_e32 v53, v53
	s_nop 0
	v_add_f32_e32 v52, 1.0, v52
	v_add_f32_e32 v53, 1.0, v53
	v_rcp_f32_e32 v52, v52
	v_rcp_f32_e32 v53, v53
	s_nop 0
	v_fma_f32 v54, v36, v52, v51
	v_sub_f32_e32 v52, 1.0, v52
	v_mul_f32_e32 v55, v36, v52
	v_mul_f32_e32 v56, v53, v64
	v_lshlrev_b32_e32 v75, 16, v75
	v_lshlrev_b32_e32 v65, 16, v65
	v_mul_f32_e32 v52, 0xbfb8aa3b, v75
	v_mul_f32_e32 v53, 0xbfb8aa3b, v65
	v_exp_f32_e32 v52, v52
	v_exp_f32_e32 v53, v53
	s_nop 0
	v_add_f32_e32 v52, 1.0, v52
	v_add_f32_e32 v53, 1.0, v53
	v_rcp_f32_e32 v52, v52
	v_rcp_f32_e32 v53, v53
	s_nop 0
	v_fma_f32 v57, v36, v52, v51
	v_sub_f32_e32 v52, 1.0, v52
	v_mul_f32_e32 v58, v36, v52
	v_mul_f32_e32 v59, v53, v65
	ds_write2st64_b32 v41, v54, v57 offset0:8 offset1:10
	ds_write2st64_b32 v41, v55, v58 offset0:24 offset1:26
	ds_write2st64_b32 v41, v56, v59 offset0:40 offset1:42
	v_lshlrev_b32_e32 v76, 16, v76
	v_lshlrev_b32_e32 v66, 16, v66
	v_mul_f32_e32 v52, 0xbfb8aa3b, v76
	v_mul_f32_e32 v53, 0xbfb8aa3b, v66
	v_exp_f32_e32 v52, v52
	v_exp_f32_e32 v53, v53
	s_nop 0
	v_add_f32_e32 v52, 1.0, v52
	v_add_f32_e32 v53, 1.0, v53
	v_rcp_f32_e32 v52, v52
	v_rcp_f32_e32 v53, v53
	s_nop 0
	v_fma_f32 v54, v36, v52, v51
	v_sub_f32_e32 v52, 1.0, v52
	v_mul_f32_e32 v55, v36, v52
	v_mul_f32_e32 v56, v53, v66
	v_lshlrev_b32_e32 v77, 16, v77
	v_lshlrev_b32_e32 v67, 16, v67
	v_mul_f32_e32 v52, 0xbfb8aa3b, v77
	v_mul_f32_e32 v53, 0xbfb8aa3b, v67
	v_exp_f32_e32 v52, v52
	v_exp_f32_e32 v53, v53
	s_nop 0
	v_add_f32_e32 v52, 1.0, v52
	v_add_f32_e32 v53, 1.0, v53
	v_rcp_f32_e32 v52, v52
	v_rcp_f32_e32 v53, v53
	s_nop 0
	v_fma_f32 v57, v36, v52, v51
	v_sub_f32_e32 v52, 1.0, v52
	v_mul_f32_e32 v58, v36, v52
	v_mul_f32_e32 v59, v53, v67
	ds_write2st64_b32 v41, v54, v57 offset0:12 offset1:14
	ds_write2st64_b32 v41, v55, v58 offset0:28 offset1:30
	ds_write2st64_b32 v41, v56, v59 offset0:44 offset1:46
